# lora decay epilogue: log1p(e), e=exp(-|z|) in (0,1], evaluated in f32 as ln2*log2(1+e) + (e-((1+e)-1))/(1+e) instead of ocml's 110-instruction double-float log1pf (precision note: ~2 ulp f32, same cla
# speedup vs baseline: 1.0252x; 1.0181x over previous
.LBB0_409:
	s_andn2_b64 vcc, exec, s[4:5]
	s_cbranch_vccnz .LBB0_411
	v_mov_b32_e32 v0, v133
	v_mov_b32_e32 v66, v133
	s_mov_b32 s4, 0xbfb8aa3b
	v_and_b32_e32 v0, 64, v0
	v_and_b32_e32 v66, 31, v66
	v_or3_b32 v0, v0, v66, s6
	v_lshlrev_b32_e32 v0, 2, v0
	global_load_dword v75, v0, s[50:51]
	global_load_dword v74, v0, s[50:51] offset:128
	v_mov_b32_e32 v0, v133
	v_mov_b32_e32 v66, v133
	s_mov_b32 s5, 0x3f2aaaab
	v_and_b32_e32 v67, 64, v66
	v_and_b32_e32 v68, 31, v0
	v_ashrrev_i32_e32 v66, 1, v66
	v_lshrrev_b32_e32 v0, 3, v0
	v_and_b32_e32 v66, 0xffffffc0, v66
	v_and_or_b32 v0, v0, 4, s9
	v_add_u32_e32 v66, v0, v66
	v_or3_b32 v0, v68, v67, s6
	v_lshlrev_b32_e32 v0, 1, v0
	v_lshl_add_u64 v[68:69], s[0:1], 0, v[0:1]
	s_mov_b32 s6, 0x3f317218
	s_mov_b32 s7, 0x7f800000
	s_mov_b32 s9, 0x33800000
	s_waitcnt vmcnt(1)
	v_add_f32_e32 v0, v50, v75
	v_max_f32_e64 v50, -v0, 0
	v_mul_f32_e64 v0, |v0|, s4
	v_exp_f32_e32 v0, v0
	s_waitcnt vmcnt(0)
	v_add_f32_e32 v34, v34, v74
	v_add_f32_e32 v67, 1.0, v0
	v_add_f32_e32 v70, -1.0, v67
	v_log_f32_e32 v71, v67
	v_rcp_f32_e32 v72, v67
	v_sub_f32_e32 v70, v0, v70
	v_mul_f32_e32 v70, v70, v72
	v_fmamk_f32 v0, v71, 0x3f317218, v70
	v_add_f32_e32 v0, v50, v0
	v_sub_f32_e32 v0, -0.5, v0
	v_mul_f32_e32 v0, 0x3fb8aa3b, v0
	v_exp_f32_e32 v0, v0
	v_ashrrev_i32_e32 v67, 31, v66
	v_lshlrev_b64 v[70:71], 10, v[66:67]
	v_lshl_add_u64 v[70:71], v[68:69], 0, v[70:71]
	v_cvt_pk_bf16_f32 v0, -v0, s0
	global_store_short v[70:71], v0, off
	v_max_f32_e64 v0, -v34, 0
	v_mul_f32_e64 v34, |v34|, s4
	v_exp_f32_e32 v34, v34
	s_nop 0
	v_add_f32_e32 v50, 1.0, v34
	v_add_f32_e32 v67, -1.0, v50
	v_log_f32_e32 v72, v50
	v_rcp_f32_e32 v73, v50
	v_sub_f32_e32 v67, v34, v67
	v_mul_f32_e32 v67, v67, v73
	v_fmamk_f32 v34, v72, 0x3f317218, v67
	v_add_f32_e32 v0, v0, v34
	v_sub_f32_e32 v0, -0.5, v0
	v_mul_f32_e32 v0, 0x3fb8aa3b, v0
	v_exp_f32_e32 v0, v0
	s_nop 0
	v_cvt_pk_bf16_f32 v0, -v0, s0
	global_store_short v[70:71], v0, off offset:64
	v_add_f32_e32 v0, v51, v75
	v_max_f32_e64 v34, -v0, 0
	v_mul_f32_e64 v0, |v0|, s4
	v_exp_f32_e32 v0, v0
	s_nop 0
	v_add_f32_e32 v50, 1.0, v0
	v_add_f32_e32 v51, -1.0, v50
	v_log_f32_e32 v67, v50
	v_rcp_f32_e32 v70, v50
	v_sub_f32_e32 v51, v0, v51
	v_mul_f32_e32 v51, v51, v70
	v_fmamk_f32 v0, v67, 0x3f317218, v51
	v_add_f32_e32 v0, v34, v0
	v_sub_f32_e32 v0, -0.5, v0
	v_mul_f32_e32 v0, 0x3fb8aa3b, v0
	v_exp_f32_e32 v0, v0
	v_or_b32_e32 v50, 1, v66
	v_ashrrev_i32_e32 v51, 31, v50
	v_lshlrev_b64 v[50:51], 10, v[50:51]
	v_cvt_pk_bf16_f32 v0, -v0, s0
	v_lshl_add_u64 v[50:51], v[68:69], 0, v[50:51]
	global_store_short v[50:51], v0, off
	v_add_f32_e32 v0, v35, v74
	v_max_f32_e64 v67, -v0, 0
	v_mul_f32_e64 v0, |v0|, s4
	v_exp_f32_e32 v0, v0
	s_nop 0
	v_add_f32_e32 v34, 1.0, v0
	v_add_f32_e32 v35, -1.0, v34
	v_log_f32_e32 v70, v34
	v_rcp_f32_e32 v71, v34
	v_sub_f32_e32 v35, v0, v35
	v_mul_f32_e32 v35, v35, v71
	v_fmamk_f32 v0, v70, 0x3f317218, v35
	v_add_f32_e32 v0, v67, v0
	v_sub_f32_e32 v0, -0.5, v0
	v_mul_f32_e32 v0, 0x3fb8aa3b, v0
	v_exp_f32_e32 v0, v0
	s_nop 0
	v_cvt_pk_bf16_f32 v0, -v0, s0
	global_store_short v[50:51], v0, off offset:64
	v_add_f32_e32 v0, v52, v75
	v_max_f32_e64 v50, -v0, 0
	v_mul_f32_e64 v0, |v0|, s4
	v_exp_f32_e32 v0, v0
	s_nop 0
	v_add_f32_e32 v34, 1.0, v0
	v_add_f32_e32 v35, -1.0, v34
	v_log_f32_e32 v51, v34
	v_rcp_f32_e32 v52, v34
	v_sub_f32_e32 v35, v0, v35
	v_mul_f32_e32 v35, v35, v52
	v_fmamk_f32 v0, v51, 0x3f317218, v35
	v_add_f32_e32 v0, v50, v0
	v_sub_f32_e32 v0, -0.5, v0
	v_mul_f32_e32 v0, 0x3fb8aa3b, v0
	v_exp_f32_e32 v0, v0
	v_or_b32_e32 v34, 2, v66
	v_ashrrev_i32_e32 v35, 31, v34
	v_lshlrev_b64 v[34:35], 10, v[34:35]
	v_cvt_pk_bf16_f32 v0, -v0, s0
	v_lshl_add_u64 v[34:35], v[68:69], 0, v[34:35]
	global_store_short v[34:35], v0, off
	v_add_f32_e32 v0, v36, v74
	v_max_f32_e64 v36, -v0, 0
	v_mul_f32_e64 v0, |v0|, s4
	v_exp_f32_e32 v0, v0
	s_nop 0
	v_add_f32_e32 v50, 1.0, v0
	v_add_f32_e32 v51, -1.0, v50
	v_log_f32_e32 v52, v50
	v_rcp_f32_e32 v67, v50
	v_sub_f32_e32 v51, v0, v51
	v_mul_f32_e32 v51, v51, v67
	v_fmamk_f32 v0, v52, 0x3f317218, v51
	v_add_f32_e32 v0, v36, v0
	v_sub_f32_e32 v0, -0.5, v0
	v_mul_f32_e32 v0, 0x3fb8aa3b, v0
	v_exp_f32_e32 v0, v0
	s_nop 0
	v_cvt_pk_bf16_f32 v0, -v0, s0
	global_store_short v[34:35], v0, off offset:64
	v_add_f32_e32 v0, v53, v75
	v_max_f32_e64 v36, -v0, 0
	v_mul_f32_e64 v0, |v0|, s4
	v_exp_f32_e32 v0, v0
	s_nop 0
	v_add_f32_e32 v34, 1.0, v0
	v_add_f32_e32 v35, -1.0, v34
	v_log_f32_e32 v50, v34
	v_rcp_f32_e32 v51, v34
	v_sub_f32_e32 v35, v0, v35
	v_mul_f32_e32 v35, v35, v51
	v_fmamk_f32 v0, v50, 0x3f317218, v35
	v_add_f32_e32 v0, v36, v0
	v_sub_f32_e32 v0, -0.5, v0
	v_mul_f32_e32 v0, 0x3fb8aa3b, v0
	v_exp_f32_e32 v0, v0
	v_or_b32_e32 v34, 3, v66
	v_ashrrev_i32_e32 v35, 31, v34
	v_lshlrev_b64 v[34:35], 10, v[34:35]
	v_cvt_pk_bf16_f32 v0, -v0, s0
	v_lshl_add_u64 v[34:35], v[68:69], 0, v[34:35]
	global_store_short v[34:35], v0, off
	v_add_f32_e32 v0, v37, v74
	v_max_f32_e64 v50, -v0, 0
	v_mul_f32_e64 v0, |v0|, s4
	v_exp_f32_e32 v0, v0
	s_nop 0
	v_add_f32_e32 v36, 1.0, v0
	v_add_f32_e32 v37, -1.0, v36
	v_log_f32_e32 v51, v36
	v_rcp_f32_e32 v52, v36
	v_sub_f32_e32 v37, v0, v37
	v_mul_f32_e32 v37, v37, v52
	v_fmamk_f32 v0, v51, 0x3f317218, v37
	v_add_f32_e32 v0, v50, v0
	v_sub_f32_e32 v0, -0.5, v0
	v_mul_f32_e32 v0, 0x3fb8aa3b, v0
	v_exp_f32_e32 v0, v0
	s_nop 0
	v_cvt_pk_bf16_f32 v0, -v0, s0
	global_store_short v[34:35], v0, off offset:64
	v_add_f32_e32 v0, v54, v75
	v_max_f32_e64 v35, -v0, 0
	v_mul_f32_e64 v0, |v0|, s4
	v_exp_f32_e32 v0, v0
	v_or_b32_e32 v34, 8, v66
	v_add_f32_e32 v36, 1.0, v0
	v_add_f32_e32 v37, -1.0, v36
	v_log_f32_e32 v50, v36
	v_rcp_f32_e32 v51, v36
	v_sub_f32_e32 v37, v0, v37
	v_mul_f32_e32 v37, v37, v51
	v_fmamk_f32 v0, v50, 0x3f317218, v37
	v_add_f32_e32 v0, v35, v0
	v_sub_f32_e32 v0, -0.5, v0
	v_mul_f32_e32 v0, 0x3fb8aa3b, v0
	v_exp_f32_e32 v0, v0
	v_ashrrev_i32_e32 v35, 31, v34
	v_lshlrev_b64 v[34:35], 10, v[34:35]
	v_lshl_add_u64 v[34:35], v[68:69], 0, v[34:35]
	v_cvt_pk_bf16_f32 v0, -v0, s0
	global_store_short v[34:35], v0, off
	v_add_f32_e32 v0, v38, v74
	v_max_f32_e64 v38, -v0, 0
	v_mul_f32_e64 v0, |v0|, s4
	v_exp_f32_e32 v0, v0
	s_nop 0
	v_add_f32_e32 v36, 1.0, v0
	v_add_f32_e32 v37, -1.0, v36
	v_log_f32_e32 v50, v36
	v_rcp_f32_e32 v51, v36
	v_sub_f32_e32 v37, v0, v37
	v_mul_f32_e32 v37, v37, v51
	v_fmamk_f32 v0, v50, 0x3f317218, v37
	v_add_f32_e32 v0, v38, v0
	v_sub_f32_e32 v0, -0.5, v0
	v_mul_f32_e32 v0, 0x3fb8aa3b, v0
	v_exp_f32_e32 v0, v0
	s_nop 0
	v_cvt_pk_bf16_f32 v0, -v0, s0
	global_store_short v[34:35], v0, off offset:64
	v_add_f32_e32 v0, v55, v75
	v_max_f32_e64 v36, -v0, 0
	v_mul_f32_e64 v0, |v0|, s4
	v_exp_f32_e32 v0, v0
	s_nop 0
	v_add_f32_e32 v34, 1.0, v0
	v_add_f32_e32 v35, -1.0, v34
	v_log_f32_e32 v37, v34
	v_rcp_f32_e32 v38, v34
	v_sub_f32_e32 v35, v0, v35
	v_mul_f32_e32 v35, v35, v38
	v_fmamk_f32 v0, v37, 0x3f317218, v35
	v_add_f32_e32 v0, v36, v0
	v_sub_f32_e32 v0, -0.5, v0
	v_mul_f32_e32 v0, 0x3fb8aa3b, v0
	v_exp_f32_e32 v0, v0
	v_or_b32_e32 v34, 9, v66
	v_ashrrev_i32_e32 v35, 31, v34
	v_lshlrev_b64 v[34:35], 10, v[34:35]
	v_cvt_pk_bf16_f32 v0, -v0, s0
	v_lshl_add_u64 v[34:35], v[68:69], 0, v[34:35]
	global_store_short v[34:35], v0, off
	v_add_f32_e32 v0, v39, v74
	v_max_f32_e64 v38, -v0, 0
	v_mul_f32_e64 v0, |v0|, s4
	v_exp_f32_e32 v0, v0
	s_nop 0
	v_add_f32_e32 v36, 1.0, v0
	v_add_f32_e32 v37, -1.0, v36
	v_log_f32_e32 v39, v36
	v_rcp_f32_e32 v50, v36
	v_sub_f32_e32 v37, v0, v37
	v_mul_f32_e32 v37, v37, v50
	v_fmamk_f32 v0, v39, 0x3f317218, v37
	v_add_f32_e32 v0, v38, v0
	v_sub_f32_e32 v0, -0.5, v0
	v_mul_f32_e32 v0, 0x3fb8aa3b, v0
	v_exp_f32_e32 v0, v0
	s_nop 0
	v_cvt_pk_bf16_f32 v0, -v0, s0
	global_store_short v[34:35], v0, off offset:64
	v_add_f32_e32 v0, v56, v75
	v_max_f32_e64 v36, -v0, 0
	v_mul_f32_e64 v0, |v0|, s4
	v_exp_f32_e32 v0, v0
	s_nop 0
	v_add_f32_e32 v34, 1.0, v0
	v_add_f32_e32 v35, -1.0, v34
	v_log_f32_e32 v37, v34
	v_rcp_f32_e32 v38, v34
	v_sub_f32_e32 v35, v0, v35
	v_mul_f32_e32 v35, v35, v38
	v_fmamk_f32 v0, v37, 0x3f317218, v35
	v_add_f32_e32 v0, v36, v0
	v_sub_f32_e32 v0, -0.5, v0
	v_mul_f32_e32 v0, 0x3fb8aa3b, v0
	v_exp_f32_e32 v0, v0
	v_or_b32_e32 v34, 10, v66
	v_ashrrev_i32_e32 v35, 31, v34
	v_lshlrev_b64 v[34:35], 10, v[34:35]
	v_cvt_pk_bf16_f32 v0, -v0, s0
	v_lshl_add_u64 v[34:35], v[68:69], 0, v[34:35]
	global_store_short v[34:35], v0, off
	v_add_f32_e32 v0, v40, v74
	v_max_f32_e64 v38, -v0, 0
	v_mul_f32_e64 v0, |v0|, s4
	v_exp_f32_e32 v0, v0
	s_nop 0
	v_add_f32_e32 v36, 1.0, v0
	v_add_f32_e32 v37, -1.0, v36
	v_log_f32_e32 v39, v36
	v_rcp_f32_e32 v40, v36
	v_sub_f32_e32 v37, v0, v37
	v_mul_f32_e32 v37, v37, v40
	v_fmamk_f32 v0, v39, 0x3f317218, v37
	v_add_f32_e32 v0, v38, v0
	v_sub_f32_e32 v0, -0.5, v0
	v_mul_f32_e32 v0, 0x3fb8aa3b, v0
	v_exp_f32_e32 v0, v0
	s_nop 0
	v_cvt_pk_bf16_f32 v0, -v0, s0
	global_store_short v[34:35], v0, off offset:64
	v_add_f32_e32 v0, v57, v75
	v_max_f32_e64 v36, -v0, 0
	v_mul_f32_e64 v0, |v0|, s4
	v_exp_f32_e32 v0, v0
	s_nop 0
	v_add_f32_e32 v34, 1.0, v0
	v_add_f32_e32 v35, -1.0, v34
	v_log_f32_e32 v37, v34
	v_rcp_f32_e32 v38, v34
	v_sub_f32_e32 v35, v0, v35
	v_mul_f32_e32 v35, v35, v38
	v_fmamk_f32 v0, v37, 0x3f317218, v35
	v_add_f32_e32 v0, v36, v0
	v_sub_f32_e32 v0, -0.5, v0
	v_mul_f32_e32 v0, 0x3fb8aa3b, v0
	v_exp_f32_e32 v0, v0
	v_or_b32_e32 v34, 11, v66
	v_ashrrev_i32_e32 v35, 31, v34
	v_lshlrev_b64 v[34:35], 10, v[34:35]
	v_cvt_pk_bf16_f32 v0, -v0, s0
	v_lshl_add_u64 v[34:35], v[68:69], 0, v[34:35]
	global_store_short v[34:35], v0, off
	v_add_f32_e32 v0, v41, v74
	v_max_f32_e64 v38, -v0, 0
	v_mul_f32_e64 v0, |v0|, s4
	v_exp_f32_e32 v0, v0
	s_nop 0
	v_add_f32_e32 v36, 1.0, v0
	v_add_f32_e32 v37, -1.0, v36
	v_log_f32_e32 v39, v36
	v_rcp_f32_e32 v40, v36
	v_sub_f32_e32 v37, v0, v37
	v_mul_f32_e32 v37, v37, v40
	v_fmamk_f32 v0, v39, 0x3f317218, v37
	v_add_f32_e32 v0, v38, v0
	v_sub_f32_e32 v0, -0.5, v0
	v_mul_f32_e32 v0, 0x3fb8aa3b, v0
	v_exp_f32_e32 v0, v0
	s_nop 0
	v_cvt_pk_bf16_f32 v0, -v0, s0
	global_store_short v[34:35], v0, off offset:64
	v_add_f32_e32 v0, v58, v75
	v_max_f32_e64 v35, -v0, 0
	v_mul_f32_e64 v0, |v0|, s4
	v_exp_f32_e32 v0, v0
	v_or_b32_e32 v34, 16, v66
	v_add_f32_e32 v36, 1.0, v0
	v_add_f32_e32 v37, -1.0, v36
	v_log_f32_e32 v38, v36
	v_rcp_f32_e32 v39, v36
	v_sub_f32_e32 v37, v0, v37
	v_mul_f32_e32 v37, v37, v39
	v_fmamk_f32 v0, v38, 0x3f317218, v37
	v_add_f32_e32 v0, v35, v0
	v_sub_f32_e32 v0, -0.5, v0
	v_mul_f32_e32 v0, 0x3fb8aa3b, v0
	v_exp_f32_e32 v0, v0
	v_ashrrev_i32_e32 v35, 31, v34
	v_lshlrev_b64 v[34:35], 10, v[34:35]
	v_lshl_add_u64 v[34:35], v[68:69], 0, v[34:35]
	v_cvt_pk_bf16_f32 v0, -v0, s0
	global_store_short v[34:35], v0, off
	v_add_f32_e32 v0, v42, v74
	v_max_f32_e64 v38, -v0, 0
	v_mul_f32_e64 v0, |v0|, s4
	v_exp_f32_e32 v0, v0
	s_nop 0
	v_add_f32_e32 v36, 1.0, v0
	v_add_f32_e32 v37, -1.0, v36
	v_log_f32_e32 v39, v36
	v_rcp_f32_e32 v40, v36
	v_sub_f32_e32 v37, v0, v37
	v_mul_f32_e32 v37, v37, v40
	v_fmamk_f32 v0, v39, 0x3f317218, v37
	v_add_f32_e32 v0, v38, v0
	v_sub_f32_e32 v0, -0.5, v0
	v_mul_f32_e32 v0, 0x3fb8aa3b, v0
	v_exp_f32_e32 v0, v0
	s_nop 0
	v_cvt_pk_bf16_f32 v0, -v0, s0
	global_store_short v[34:35], v0, off offset:64
	v_add_f32_e32 v0, v59, v75
	v_max_f32_e64 v36, -v0, 0
	v_mul_f32_e64 v0, |v0|, s4
	v_exp_f32_e32 v0, v0
	s_nop 0
	v_add_f32_e32 v34, 1.0, v0
	v_add_f32_e32 v35, -1.0, v34
	v_log_f32_e32 v37, v34
	v_rcp_f32_e32 v38, v34
	v_sub_f32_e32 v35, v0, v35
	v_mul_f32_e32 v35, v35, v38
	v_fmamk_f32 v0, v37, 0x3f317218, v35
	v_add_f32_e32 v0, v36, v0
	v_sub_f32_e32 v0, -0.5, v0
	v_mul_f32_e32 v0, 0x3fb8aa3b, v0
	v_exp_f32_e32 v0, v0
	v_or_b32_e32 v34, 17, v66
	v_ashrrev_i32_e32 v35, 31, v34
	v_lshlrev_b64 v[34:35], 10, v[34:35]
	v_cvt_pk_bf16_f32 v0, -v0, s0
	v_lshl_add_u64 v[34:35], v[68:69], 0, v[34:35]
	global_store_short v[34:35], v0, off
	v_add_f32_e32 v0, v43, v74
	v_max_f32_e64 v38, -v0, 0
	v_mul_f32_e64 v0, |v0|, s4
	v_exp_f32_e32 v0, v0
	s_nop 0
	v_add_f32_e32 v36, 1.0, v0
	v_add_f32_e32 v37, -1.0, v36
	v_log_f32_e32 v39, v36
	v_rcp_f32_e32 v40, v36
	v_sub_f32_e32 v37, v0, v37
	v_mul_f32_e32 v37, v37, v40
	v_fmamk_f32 v0, v39, 0x3f317218, v37
	v_add_f32_e32 v0, v38, v0
	v_sub_f32_e32 v0, -0.5, v0
	v_mul_f32_e32 v0, 0x3fb8aa3b, v0
	v_exp_f32_e32 v0, v0
	s_nop 0
	v_cvt_pk_bf16_f32 v0, -v0, s0
	global_store_short v[34:35], v0, off offset:64
	v_add_f32_e32 v0, v60, v75
	v_max_f32_e64 v36, -v0, 0
	v_mul_f32_e64 v0, |v0|, s4
	v_exp_f32_e32 v0, v0
	s_nop 0
	v_add_f32_e32 v34, 1.0, v0
	v_add_f32_e32 v35, -1.0, v34
	v_log_f32_e32 v37, v34
	v_rcp_f32_e32 v38, v34
	v_sub_f32_e32 v35, v0, v35
	v_mul_f32_e32 v35, v35, v38
	v_fmamk_f32 v0, v37, 0x3f317218, v35
	v_add_f32_e32 v0, v36, v0
	v_sub_f32_e32 v0, -0.5, v0
	v_mul_f32_e32 v0, 0x3fb8aa3b, v0
	v_exp_f32_e32 v0, v0
	v_or_b32_e32 v34, 18, v66
	v_ashrrev_i32_e32 v35, 31, v34
	v_lshlrev_b64 v[34:35], 10, v[34:35]
	v_cvt_pk_bf16_f32 v0, -v0, s0
	v_lshl_add_u64 v[34:35], v[68:69], 0, v[34:35]
	global_store_short v[34:35], v0, off
	v_add_f32_e32 v0, v44, v74
	v_max_f32_e64 v38, -v0, 0
	v_mul_f32_e64 v0, |v0|, s4
	v_exp_f32_e32 v0, v0
	s_nop 0
	v_add_f32_e32 v36, 1.0, v0
	v_add_f32_e32 v37, -1.0, v36
	v_log_f32_e32 v39, v36
	v_rcp_f32_e32 v40, v36
	v_sub_f32_e32 v37, v0, v37
	v_mul_f32_e32 v37, v37, v40
	v_fmamk_f32 v0, v39, 0x3f317218, v37
	v_add_f32_e32 v0, v38, v0
	v_sub_f32_e32 v0, -0.5, v0
	v_mul_f32_e32 v0, 0x3fb8aa3b, v0
	v_exp_f32_e32 v0, v0
	s_nop 0
	v_cvt_pk_bf16_f32 v0, -v0, s0
	global_store_short v[34:35], v0, off offset:64
	v_add_f32_e32 v0, v61, v75
	v_max_f32_e64 v36, -v0, 0
	v_mul_f32_e64 v0, |v0|, s4
	v_exp_f32_e32 v0, v0
	s_nop 0
	v_add_f32_e32 v34, 1.0, v0
	v_add_f32_e32 v35, -1.0, v34
	v_log_f32_e32 v37, v34
	v_rcp_f32_e32 v38, v34
	v_sub_f32_e32 v35, v0, v35
	v_mul_f32_e32 v35, v35, v38
	v_fmamk_f32 v0, v37, 0x3f317218, v35
	v_add_f32_e32 v0, v36, v0
	v_sub_f32_e32 v0, -0.5, v0
	v_mul_f32_e32 v0, 0x3fb8aa3b, v0
	v_exp_f32_e32 v0, v0
	v_or_b32_e32 v34, 19, v66
	v_ashrrev_i32_e32 v35, 31, v34
	v_lshlrev_b64 v[34:35], 10, v[34:35]
	v_cvt_pk_bf16_f32 v0, -v0, s0
	v_lshl_add_u64 v[34:35], v[68:69], 0, v[34:35]
	global_store_short v[34:35], v0, off
	v_add_f32_e32 v0, v45, v74
	v_max_f32_e64 v38, -v0, 0
	v_mul_f32_e64 v0, |v0|, s4
	v_exp_f32_e32 v0, v0
	s_nop 0
	v_add_f32_e32 v36, 1.0, v0
	v_add_f32_e32 v37, -1.0, v36
	v_log_f32_e32 v39, v36
	v_rcp_f32_e32 v40, v36
	v_sub_f32_e32 v37, v0, v37
	v_mul_f32_e32 v37, v37, v40
	v_fmamk_f32 v0, v39, 0x3f317218, v37
	v_add_f32_e32 v0, v38, v0
	v_sub_f32_e32 v0, -0.5, v0
	v_mul_f32_e32 v0, 0x3fb8aa3b, v0
	v_exp_f32_e32 v0, v0
	s_nop 0
	v_cvt_pk_bf16_f32 v0, -v0, s0
	global_store_short v[34:35], v0, off offset:64
	v_add_f32_e32 v0, v62, v75
	v_max_f32_e64 v35, -v0, 0
	v_mul_f32_e64 v0, |v0|, s4
	v_exp_f32_e32 v0, v0
	v_or_b32_e32 v34, 24, v66
	v_add_f32_e32 v36, 1.0, v0
	v_add_f32_e32 v37, -1.0, v36
	v_log_f32_e32 v38, v36
	v_rcp_f32_e32 v39, v36
	v_sub_f32_e32 v37, v0, v37
	v_mul_f32_e32 v37, v37, v39
	v_fmamk_f32 v0, v38, 0x3f317218, v37
	v_add_f32_e32 v0, v35, v0
	v_sub_f32_e32 v0, -0.5, v0
	v_mul_f32_e32 v0, 0x3fb8aa3b, v0
	v_exp_f32_e32 v0, v0
	v_ashrrev_i32_e32 v35, 31, v34
	v_lshlrev_b64 v[34:35], 10, v[34:35]
	v_lshl_add_u64 v[34:35], v[68:69], 0, v[34:35]
	v_cvt_pk_bf16_f32 v0, -v0, s0
	global_store_short v[34:35], v0, off
	v_add_f32_e32 v0, v46, v74
	v_max_f32_e64 v38, -v0, 0
	v_mul_f32_e64 v0, |v0|, s4
	v_exp_f32_e32 v0, v0
	s_nop 0
	v_add_f32_e32 v36, 1.0, v0
	v_add_f32_e32 v37, -1.0, v36
	v_log_f32_e32 v39, v36
	v_rcp_f32_e32 v40, v36
	v_sub_f32_e32 v37, v0, v37
	v_mul_f32_e32 v37, v37, v40
	v_fmamk_f32 v0, v39, 0x3f317218, v37
	v_add_f32_e32 v0, v38, v0
	v_sub_f32_e32 v0, -0.5, v0
	v_mul_f32_e32 v0, 0x3fb8aa3b, v0
	v_exp_f32_e32 v0, v0
	s_nop 0
	v_cvt_pk_bf16_f32 v0, -v0, s0
	global_store_short v[34:35], v0, off offset:64
	v_add_f32_e32 v0, v63, v75
	v_max_f32_e64 v36, -v0, 0
	v_mul_f32_e64 v0, |v0|, s4
	v_exp_f32_e32 v0, v0
	s_nop 0
	v_add_f32_e32 v34, 1.0, v0
	v_add_f32_e32 v35, -1.0, v34
	v_log_f32_e32 v37, v34
	v_rcp_f32_e32 v38, v34
	v_sub_f32_e32 v35, v0, v35
	v_mul_f32_e32 v35, v35, v38
	v_fmamk_f32 v0, v37, 0x3f317218, v35
	v_add_f32_e32 v0, v36, v0
	v_sub_f32_e32 v0, -0.5, v0
	v_mul_f32_e32 v0, 0x3fb8aa3b, v0
	v_exp_f32_e32 v0, v0
	v_or_b32_e32 v34, 25, v66
	v_ashrrev_i32_e32 v35, 31, v34
	v_lshlrev_b64 v[34:35], 10, v[34:35]
	v_cvt_pk_bf16_f32 v0, -v0, s0
	v_lshl_add_u64 v[34:35], v[68:69], 0, v[34:35]
	global_store_short v[34:35], v0, off
	v_add_f32_e32 v0, v47, v74
	v_max_f32_e64 v38, -v0, 0
	v_mul_f32_e64 v0, |v0|, s4
	v_exp_f32_e32 v0, v0
	s_nop 0
	v_add_f32_e32 v36, 1.0, v0
	v_add_f32_e32 v37, -1.0, v36
	v_log_f32_e32 v39, v36
	v_rcp_f32_e32 v40, v36
	v_sub_f32_e32 v37, v0, v37
	v_mul_f32_e32 v37, v37, v40
	v_fmamk_f32 v0, v39, 0x3f317218, v37
	v_add_f32_e32 v0, v38, v0
	v_sub_f32_e32 v0, -0.5, v0
	v_mul_f32_e32 v0, 0x3fb8aa3b, v0
	v_exp_f32_e32 v0, v0
	s_nop 0
	v_cvt_pk_bf16_f32 v0, -v0, s0
	global_store_short v[34:35], v0, off offset:64
	v_add_f32_e32 v0, v64, v75
	v_max_f32_e64 v36, -v0, 0
	v_mul_f32_e64 v0, |v0|, s4
	v_exp_f32_e32 v0, v0
	s_nop 0
	v_add_f32_e32 v34, 1.0, v0
	v_add_f32_e32 v35, -1.0, v34
	v_log_f32_e32 v37, v34
	v_rcp_f32_e32 v38, v34
	v_sub_f32_e32 v35, v0, v35
	v_mul_f32_e32 v35, v35, v38
	v_fmamk_f32 v0, v37, 0x3f317218, v35
	v_add_f32_e32 v0, v36, v0
	v_sub_f32_e32 v0, -0.5, v0
	v_mul_f32_e32 v0, 0x3fb8aa3b, v0
	v_exp_f32_e32 v0, v0
	v_or_b32_e32 v34, 26, v66
	v_ashrrev_i32_e32 v35, 31, v34
	v_lshlrev_b64 v[34:35], 10, v[34:35]
	v_cvt_pk_bf16_f32 v0, -v0, s0
	v_lshl_add_u64 v[34:35], v[68:69], 0, v[34:35]
	global_store_short v[34:35], v0, off
	v_add_f32_e32 v0, v48, v74
	v_max_f32_e64 v38, -v0, 0
	v_mul_f32_e64 v0, |v0|, s4
	v_exp_f32_e32 v0, v0
	s_nop 0
	v_add_f32_e32 v36, 1.0, v0
	v_add_f32_e32 v37, -1.0, v36
	v_log_f32_e32 v39, v36
	v_rcp_f32_e32 v40, v36
	v_sub_f32_e32 v37, v0, v37
	v_mul_f32_e32 v37, v37, v40
	v_fmamk_f32 v0, v39, 0x3f317218, v37
	v_add_f32_e32 v0, v38, v0
	v_sub_f32_e32 v0, -0.5, v0
	v_mul_f32_e32 v0, 0x3fb8aa3b, v0
	v_exp_f32_e32 v0, v0
	s_nop 0
	v_cvt_pk_bf16_f32 v0, -v0, s0
	global_store_short v[34:35], v0, off offset:64
	v_add_f32_e32 v0, v65, v75
	v_max_f32_e64 v36, -v0, 0
	v_mul_f32_e64 v0, |v0|, s4
	v_exp_f32_e32 v0, v0
	s_nop 0
	v_add_f32_e32 v34, 1.0, v0
	v_add_f32_e32 v35, -1.0, v34
	v_log_f32_e32 v37, v34
	v_rcp_f32_e32 v38, v34
	v_sub_f32_e32 v35, v0, v35
	v_mul_f32_e32 v35, v35, v38
	v_fmamk_f32 v0, v37, 0x3f317218, v35
	v_add_f32_e32 v0, v36, v0
	v_sub_f32_e32 v0, -0.5, v0
	v_mul_f32_e32 v0, 0x3fb8aa3b, v0
	v_exp_f32_e32 v0, v0
	v_or_b32_e32 v34, 27, v66
	v_ashrrev_i32_e32 v35, 31, v34
	v_lshlrev_b64 v[34:35], 10, v[34:35]
	v_cvt_pk_bf16_f32 v0, -v0, s0
	v_lshl_add_u64 v[34:35], v[68:69], 0, v[34:35]
	global_store_short v[34:35], v0, off
	v_add_f32_e32 v0, v49, v74
	v_max_f32_e64 v38, -v0, 0
	v_mul_f32_e64 v0, |v0|, s4
	v_exp_f32_e32 v0, v0
	s_nop 0
	v_add_f32_e32 v36, 1.0, v0
	v_add_f32_e32 v37, -1.0, v36
	v_log_f32_e32 v39, v36
	v_rcp_f32_e32 v40, v36
	v_sub_f32_e32 v37, v0, v37
	v_mul_f32_e32 v37, v37, v40
	v_fmamk_f32 v0, v39, 0x3f317218, v37
	v_add_f32_e32 v0, v38, v0
	v_sub_f32_e32 v0, -0.5, v0
	v_mul_f32_e32 v0, 0x3fb8aa3b, v0
	v_exp_f32_e32 v0, v0
	s_nop 0
	v_cvt_pk_bf16_f32 v0, -v0, s0
	global_store_short v[34:35], v0, off offset:64
	v_add_f32_e32 v0, v18, v75
	v_max_f32_e64 v18, -v0, 0
	v_mul_f32_e64 v0, |v0|, s4
	v_exp_f32_e32 v0, v0
	v_or_b32_e32 v34, 32, v66
	v_add_f32_e32 v35, 1.0, v0
	v_add_f32_e32 v36, -1.0, v35
	v_log_f32_e32 v37, v35
	v_rcp_f32_e32 v38, v35
	v_sub_f32_e32 v36, v0, v36
	v_mul_f32_e32 v36, v36, v38
	v_fmamk_f32 v0, v37, 0x3f317218, v36
	v_add_f32_e32 v0, v18, v0
	v_sub_f32_e32 v0, -0.5, v0
	v_mul_f32_e32 v0, 0x3fb8aa3b, v0
	v_exp_f32_e32 v0, v0
	v_ashrrev_i32_e32 v35, 31, v34
	v_lshlrev_b64 v[34:35], 10, v[34:35]
	v_lshl_add_u64 v[34:35], v[68:69], 0, v[34:35]
	v_cvt_pk_bf16_f32 v0, -v0, s0
	global_store_short v[34:35], v0, off
	v_add_f32_e32 v0, v2, v74
	v_max_f32_e64 v2, -v0, 0
	v_mul_f32_e64 v0, |v0|, s4
	v_exp_f32_e32 v0, v0
	s_nop 0
	v_add_f32_e32 v18, 1.0, v0
	v_add_f32_e32 v36, -1.0, v18
	v_log_f32_e32 v37, v18
	v_rcp_f32_e32 v38, v18
	v_sub_f32_e32 v36, v0, v36
	v_mul_f32_e32 v36, v36, v38
	v_fmamk_f32 v0, v37, 0x3f317218, v36
	v_add_f32_e32 v0, v2, v0
	v_sub_f32_e32 v0, -0.5, v0
	v_mul_f32_e32 v0, 0x3fb8aa3b, v0
	v_exp_f32_e32 v0, v0
	s_nop 0
	v_cvt_pk_bf16_f32 v0, -v0, s0
	global_store_short v[34:35], v0, off offset:64
	v_add_f32_e32 v0, v19, v75
	v_max_f32_e64 v2, -v0, 0
	v_mul_f32_e64 v0, |v0|, s4
	v_exp_f32_e32 v0, v0
	s_nop 0
	v_add_f32_e32 v18, 1.0, v0
	v_add_f32_e32 v19, -1.0, v18
	v_log_f32_e32 v34, v18
	v_rcp_f32_e32 v35, v18
	v_sub_f32_e32 v19, v0, v19
	v_mul_f32_e32 v19, v19, v35
	v_fmamk_f32 v0, v34, 0x3f317218, v19
	v_add_f32_e32 v0, v2, v0
	v_sub_f32_e32 v0, -0.5, v0
	v_mul_f32_e32 v0, 0x3fb8aa3b, v0
	v_exp_f32_e32 v0, v0
	v_or_b32_e32 v18, 33, v66
	v_ashrrev_i32_e32 v19, 31, v18
	v_lshlrev_b64 v[18:19], 10, v[18:19]
	v_cvt_pk_bf16_f32 v0, -v0, s0
	v_lshl_add_u64 v[18:19], v[68:69], 0, v[18:19]
	global_store_short v[18:19], v0, off
	v_add_f32_e32 v0, v3, v74
	v_max_f32_e64 v34, -v0, 0
	v_mul_f32_e64 v0, |v0|, s4
	v_exp_f32_e32 v0, v0
	s_nop 0
	v_add_f32_e32 v2, 1.0, v0
	v_add_f32_e32 v3, -1.0, v2
	v_log_f32_e32 v35, v2
	v_rcp_f32_e32 v36, v2
	v_sub_f32_e32 v3, v0, v3
	v_mul_f32_e32 v3, v3, v36
	v_fmamk_f32 v0, v35, 0x3f317218, v3
	v_add_f32_e32 v0, v34, v0
	v_sub_f32_e32 v0, -0.5, v0
	v_mul_f32_e32 v0, 0x3fb8aa3b, v0
	v_exp_f32_e32 v0, v0
	s_nop 0
	v_cvt_pk_bf16_f32 v0, -v0, s0
	global_store_short v[18:19], v0, off offset:64
	v_add_f32_e32 v0, v20, v75
	v_max_f32_e64 v18, -v0, 0
	v_mul_f32_e64 v0, |v0|, s4
	v_exp_f32_e32 v0, v0
	s_nop 0
	v_add_f32_e32 v2, 1.0, v0
	v_add_f32_e32 v3, -1.0, v2
	v_log_f32_e32 v19, v2
	v_rcp_f32_e32 v20, v2
	v_sub_f32_e32 v3, v0, v3
	v_mul_f32_e32 v3, v3, v20
	v_fmamk_f32 v0, v19, 0x3f317218, v3
	v_add_f32_e32 v0, v18, v0
	v_sub_f32_e32 v0, -0.5, v0
	v_mul_f32_e32 v0, 0x3fb8aa3b, v0
	v_exp_f32_e32 v0, v0
	v_or_b32_e32 v2, 34, v66
	v_ashrrev_i32_e32 v3, 31, v2
	v_lshlrev_b64 v[2:3], 10, v[2:3]
	v_cvt_pk_bf16_f32 v0, -v0, s0
	v_lshl_add_u64 v[2:3], v[68:69], 0, v[2:3]
	global_store_short v[2:3], v0, off
	v_add_f32_e32 v0, v4, v74
	v_max_f32_e64 v4, -v0, 0
	v_mul_f32_e64 v0, |v0|, s4
	v_exp_f32_e32 v0, v0
	s_nop 0
	v_add_f32_e32 v18, 1.0, v0
	v_add_f32_e32 v19, -1.0, v18
	v_log_f32_e32 v20, v18
	v_rcp_f32_e32 v34, v18
	v_sub_f32_e32 v19, v0, v19
	v_mul_f32_e32 v19, v19, v34
	v_fmamk_f32 v0, v20, 0x3f317218, v19
	v_add_f32_e32 v0, v4, v0
	v_sub_f32_e32 v0, -0.5, v0
	v_mul_f32_e32 v0, 0x3fb8aa3b, v0
	v_exp_f32_e32 v0, v0
	s_nop 0
	v_cvt_pk_bf16_f32 v0, -v0, s0
	global_store_short v[2:3], v0, off offset:64
	v_add_f32_e32 v0, v21, v75
	v_max_f32_e64 v4, -v0, 0
	v_mul_f32_e64 v0, |v0|, s4
	v_exp_f32_e32 v0, v0
	s_nop 0
	v_add_f32_e32 v2, 1.0, v0
	v_add_f32_e32 v3, -1.0, v2
	v_log_f32_e32 v18, v2
	v_rcp_f32_e32 v19, v2
	v_sub_f32_e32 v3, v0, v3
	v_mul_f32_e32 v3, v3, v19
	v_fmamk_f32 v0, v18, 0x3f317218, v3
	v_add_f32_e32 v0, v4, v0
	v_sub_f32_e32 v0, -0.5, v0
	v_mul_f32_e32 v0, 0x3fb8aa3b, v0
	v_exp_f32_e32 v0, v0
	v_or_b32_e32 v2, 35, v66
	v_ashrrev_i32_e32 v3, 31, v2
	v_lshlrev_b64 v[2:3], 10, v[2:3]
	v_cvt_pk_bf16_f32 v0, -v0, s0
	v_lshl_add_u64 v[2:3], v[68:69], 0, v[2:3]
	global_store_short v[2:3], v0, off
	v_add_f32_e32 v0, v5, v74
	v_max_f32_e64 v18, -v0, 0
	v_mul_f32_e64 v0, |v0|, s4
	v_exp_f32_e32 v0, v0
	s_nop 0
	v_add_f32_e32 v4, 1.0, v0
	v_add_f32_e32 v5, -1.0, v4
	v_log_f32_e32 v19, v4
	v_rcp_f32_e32 v20, v4
	v_sub_f32_e32 v5, v0, v5
	v_mul_f32_e32 v5, v5, v20
	v_fmamk_f32 v0, v19, 0x3f317218, v5
	v_add_f32_e32 v0, v18, v0
	v_sub_f32_e32 v0, -0.5, v0
	v_mul_f32_e32 v0, 0x3fb8aa3b, v0
	v_exp_f32_e32 v0, v0
	s_nop 0
	v_cvt_pk_bf16_f32 v0, -v0, s0
	global_store_short v[2:3], v0, off offset:64
	v_add_f32_e32 v0, v22, v75
	v_max_f32_e64 v3, -v0, 0
	v_mul_f32_e64 v0, |v0|, s4
	v_exp_f32_e32 v0, v0
	v_or_b32_e32 v2, 40, v66
	v_add_f32_e32 v4, 1.0, v0
	v_add_f32_e32 v5, -1.0, v4
	v_log_f32_e32 v18, v4
	v_rcp_f32_e32 v19, v4
	v_sub_f32_e32 v5, v0, v5
	v_mul_f32_e32 v5, v5, v19
	v_fmamk_f32 v0, v18, 0x3f317218, v5
	v_add_f32_e32 v0, v3, v0
	v_sub_f32_e32 v0, -0.5, v0
	v_mul_f32_e32 v0, 0x3fb8aa3b, v0
	v_exp_f32_e32 v0, v0
	v_ashrrev_i32_e32 v3, 31, v2
	v_lshlrev_b64 v[2:3], 10, v[2:3]
	v_lshl_add_u64 v[2:3], v[68:69], 0, v[2:3]
	v_cvt_pk_bf16_f32 v0, -v0, s0
	global_store_short v[2:3], v0, off
	v_add_f32_e32 v0, v6, v74
	v_max_f32_e64 v6, -v0, 0
	v_mul_f32_e64 v0, |v0|, s4
	v_exp_f32_e32 v0, v0
	s_nop 0
	v_add_f32_e32 v4, 1.0, v0
	v_add_f32_e32 v5, -1.0, v4
	v_log_f32_e32 v18, v4
	v_rcp_f32_e32 v19, v4
	v_sub_f32_e32 v5, v0, v5
	v_mul_f32_e32 v5, v5, v19
	v_fmamk_f32 v0, v18, 0x3f317218, v5
	v_add_f32_e32 v0, v6, v0
	v_sub_f32_e32 v0, -0.5, v0
	v_mul_f32_e32 v0, 0x3fb8aa3b, v0
	v_exp_f32_e32 v0, v0
	s_nop 0
	v_cvt_pk_bf16_f32 v0, -v0, s0
	global_store_short v[2:3], v0, off offset:64
	v_add_f32_e32 v0, v23, v75
	v_max_f32_e64 v4, -v0, 0
	v_mul_f32_e64 v0, |v0|, s4
	v_exp_f32_e32 v0, v0
	s_nop 0
	v_add_f32_e32 v2, 1.0, v0
	v_add_f32_e32 v3, -1.0, v2
	v_log_f32_e32 v5, v2
	v_rcp_f32_e32 v6, v2
	v_sub_f32_e32 v3, v0, v3
	v_mul_f32_e32 v3, v3, v6
	v_fmamk_f32 v0, v5, 0x3f317218, v3
	v_add_f32_e32 v0, v4, v0
	v_sub_f32_e32 v0, -0.5, v0
	v_mul_f32_e32 v0, 0x3fb8aa3b, v0
	v_exp_f32_e32 v0, v0
	v_or_b32_e32 v2, 41, v66
	v_ashrrev_i32_e32 v3, 31, v2
	v_lshlrev_b64 v[2:3], 10, v[2:3]
	v_cvt_pk_bf16_f32 v0, -v0, s0
	v_lshl_add_u64 v[2:3], v[68:69], 0, v[2:3]
	global_store_short v[2:3], v0, off
	v_add_f32_e32 v0, v7, v74
	v_max_f32_e64 v6, -v0, 0
	v_mul_f32_e64 v0, |v0|, s4
	v_exp_f32_e32 v0, v0
	s_nop 0
	v_add_f32_e32 v4, 1.0, v0
	v_add_f32_e32 v5, -1.0, v4
	v_log_f32_e32 v7, v4
	v_rcp_f32_e32 v18, v4
	v_sub_f32_e32 v5, v0, v5
	v_mul_f32_e32 v5, v5, v18
	v_fmamk_f32 v0, v7, 0x3f317218, v5
	v_add_f32_e32 v0, v6, v0
	v_sub_f32_e32 v0, -0.5, v0
	v_mul_f32_e32 v0, 0x3fb8aa3b, v0
	v_exp_f32_e32 v0, v0
	s_nop 0
	v_cvt_pk_bf16_f32 v0, -v0, s0
	global_store_short v[2:3], v0, off offset:64
	v_add_f32_e32 v0, v24, v75
	v_max_f32_e64 v4, -v0, 0
	v_mul_f32_e64 v0, |v0|, s4
	v_exp_f32_e32 v0, v0
	s_nop 0
	v_add_f32_e32 v2, 1.0, v0
	v_add_f32_e32 v3, -1.0, v2
	v_log_f32_e32 v5, v2
	v_rcp_f32_e32 v6, v2
	v_sub_f32_e32 v3, v0, v3
	v_mul_f32_e32 v3, v3, v6
	v_fmamk_f32 v0, v5, 0x3f317218, v3
	v_add_f32_e32 v0, v4, v0
	v_sub_f32_e32 v0, -0.5, v0
	v_mul_f32_e32 v0, 0x3fb8aa3b, v0
	v_exp_f32_e32 v0, v0
	v_or_b32_e32 v2, 42, v66
	v_ashrrev_i32_e32 v3, 31, v2
	v_lshlrev_b64 v[2:3], 10, v[2:3]
	v_cvt_pk_bf16_f32 v0, -v0, s0
	v_lshl_add_u64 v[2:3], v[68:69], 0, v[2:3]
	global_store_short v[2:3], v0, off
	v_add_f32_e32 v0, v8, v74
	v_max_f32_e64 v6, -v0, 0
	v_mul_f32_e64 v0, |v0|, s4
	v_exp_f32_e32 v0, v0
	s_nop 0
	v_add_f32_e32 v4, 1.0, v0
	v_add_f32_e32 v5, -1.0, v4
	v_log_f32_e32 v7, v4
	v_rcp_f32_e32 v8, v4
	v_sub_f32_e32 v5, v0, v5
	v_mul_f32_e32 v5, v5, v8
	v_fmamk_f32 v0, v7, 0x3f317218, v5
	v_add_f32_e32 v0, v6, v0
	v_sub_f32_e32 v0, -0.5, v0
	v_mul_f32_e32 v0, 0x3fb8aa3b, v0
	v_exp_f32_e32 v0, v0
	s_nop 0
	v_cvt_pk_bf16_f32 v0, -v0, s0
	global_store_short v[2:3], v0, off offset:64
	v_add_f32_e32 v0, v25, v75
	v_max_f32_e64 v4, -v0, 0
	v_mul_f32_e64 v0, |v0|, s4
	v_exp_f32_e32 v0, v0
	s_nop 0
	v_add_f32_e32 v2, 1.0, v0
	v_add_f32_e32 v3, -1.0, v2
	v_log_f32_e32 v5, v2
	v_rcp_f32_e32 v6, v2
	v_sub_f32_e32 v3, v0, v3
	v_mul_f32_e32 v3, v3, v6
	v_fmamk_f32 v0, v5, 0x3f317218, v3
	v_add_f32_e32 v0, v4, v0
	v_sub_f32_e32 v0, -0.5, v0
	v_mul_f32_e32 v0, 0x3fb8aa3b, v0
	v_exp_f32_e32 v0, v0
	v_or_b32_e32 v2, 43, v66
	v_ashrrev_i32_e32 v3, 31, v2
	v_lshlrev_b64 v[2:3], 10, v[2:3]
	v_cvt_pk_bf16_f32 v0, -v0, s0
	v_lshl_add_u64 v[2:3], v[68:69], 0, v[2:3]
	global_store_short v[2:3], v0, off
	v_add_f32_e32 v0, v9, v74
	v_max_f32_e64 v6, -v0, 0
	v_mul_f32_e64 v0, |v0|, s4
	v_exp_f32_e32 v0, v0
	s_nop 0
	v_add_f32_e32 v4, 1.0, v0
	v_add_f32_e32 v5, -1.0, v4
	v_log_f32_e32 v7, v4
	v_rcp_f32_e32 v8, v4
	v_sub_f32_e32 v5, v0, v5
	v_mul_f32_e32 v5, v5, v8
	v_fmamk_f32 v0, v7, 0x3f317218, v5
	v_add_f32_e32 v0, v6, v0
	v_sub_f32_e32 v0, -0.5, v0
	v_mul_f32_e32 v0, 0x3fb8aa3b, v0
	v_exp_f32_e32 v0, v0
	s_nop 0
	v_cvt_pk_bf16_f32 v0, -v0, s0
	global_store_short v[2:3], v0, off offset:64
	v_add_f32_e32 v0, v26, v75
	v_max_f32_e64 v3, -v0, 0
	v_mul_f32_e64 v0, |v0|, s4
	v_exp_f32_e32 v0, v0
	v_or_b32_e32 v2, 48, v66
	v_add_f32_e32 v4, 1.0, v0
	v_add_f32_e32 v5, -1.0, v4
	v_log_f32_e32 v6, v4
	v_rcp_f32_e32 v7, v4
	v_sub_f32_e32 v5, v0, v5
	v_mul_f32_e32 v5, v5, v7
	v_fmamk_f32 v0, v6, 0x3f317218, v5
	v_add_f32_e32 v0, v3, v0
	v_sub_f32_e32 v0, -0.5, v0
	v_mul_f32_e32 v0, 0x3fb8aa3b, v0
	v_exp_f32_e32 v0, v0
	v_ashrrev_i32_e32 v3, 31, v2
	v_lshlrev_b64 v[2:3], 10, v[2:3]
	v_lshl_add_u64 v[2:3], v[68:69], 0, v[2:3]
	v_cvt_pk_bf16_f32 v0, -v0, s0
	global_store_short v[2:3], v0, off
	v_add_f32_e32 v0, v10, v74
	v_max_f32_e64 v6, -v0, 0
	v_mul_f32_e64 v0, |v0|, s4
	v_exp_f32_e32 v0, v0
	s_nop 0
	v_add_f32_e32 v4, 1.0, v0
	v_add_f32_e32 v5, -1.0, v4
	v_log_f32_e32 v7, v4
	v_rcp_f32_e32 v8, v4
	v_sub_f32_e32 v5, v0, v5
	v_mul_f32_e32 v5, v5, v8
	v_fmamk_f32 v0, v7, 0x3f317218, v5
	v_add_f32_e32 v0, v6, v0
	v_sub_f32_e32 v0, -0.5, v0
	v_mul_f32_e32 v0, 0x3fb8aa3b, v0
	v_exp_f32_e32 v0, v0
	s_nop 0
	v_cvt_pk_bf16_f32 v0, -v0, s0
	global_store_short v[2:3], v0, off offset:64
	v_add_f32_e32 v0, v27, v75
	v_max_f32_e64 v4, -v0, 0
	v_mul_f32_e64 v0, |v0|, s4
	v_exp_f32_e32 v0, v0
	s_nop 0
	v_add_f32_e32 v2, 1.0, v0
	v_add_f32_e32 v3, -1.0, v2
	v_log_f32_e32 v5, v2
	v_rcp_f32_e32 v6, v2
	v_sub_f32_e32 v3, v0, v3
	v_mul_f32_e32 v3, v3, v6
	v_fmamk_f32 v0, v5, 0x3f317218, v3
	v_add_f32_e32 v0, v4, v0
	v_sub_f32_e32 v0, -0.5, v0
	v_mul_f32_e32 v0, 0x3fb8aa3b, v0
	v_exp_f32_e32 v0, v0
	v_or_b32_e32 v2, 49, v66
	v_ashrrev_i32_e32 v3, 31, v2
	v_lshlrev_b64 v[2:3], 10, v[2:3]
	v_cvt_pk_bf16_f32 v0, -v0, s0
	v_lshl_add_u64 v[2:3], v[68:69], 0, v[2:3]
	global_store_short v[2:3], v0, off
	v_add_f32_e32 v0, v11, v74
	v_max_f32_e64 v6, -v0, 0
	v_mul_f32_e64 v0, |v0|, s4
	v_exp_f32_e32 v0, v0
	s_nop 0
	v_add_f32_e32 v4, 1.0, v0
	v_add_f32_e32 v5, -1.0, v4
	v_log_f32_e32 v7, v4
	v_rcp_f32_e32 v8, v4
	v_sub_f32_e32 v5, v0, v5
	v_mul_f32_e32 v5, v5, v8
	v_fmamk_f32 v0, v7, 0x3f317218, v5
	v_add_f32_e32 v0, v6, v0
	v_sub_f32_e32 v0, -0.5, v0
	v_mul_f32_e32 v0, 0x3fb8aa3b, v0
	v_exp_f32_e32 v0, v0
	s_nop 0
	v_cvt_pk_bf16_f32 v0, -v0, s0
	global_store_short v[2:3], v0, off offset:64
	v_add_f32_e32 v0, v28, v75
	v_max_f32_e64 v4, -v0, 0
	v_mul_f32_e64 v0, |v0|, s4
	v_exp_f32_e32 v0, v0
	s_nop 0
	v_add_f32_e32 v2, 1.0, v0
	v_add_f32_e32 v3, -1.0, v2
	v_log_f32_e32 v5, v2
	v_rcp_f32_e32 v6, v2
	v_sub_f32_e32 v3, v0, v3
	v_mul_f32_e32 v3, v3, v6
	v_fmamk_f32 v0, v5, 0x3f317218, v3
	v_add_f32_e32 v0, v4, v0
	v_sub_f32_e32 v0, -0.5, v0
	v_mul_f32_e32 v0, 0x3fb8aa3b, v0
	v_exp_f32_e32 v0, v0
	v_or_b32_e32 v2, 50, v66
	v_ashrrev_i32_e32 v3, 31, v2
	v_lshlrev_b64 v[2:3], 10, v[2:3]
	v_cvt_pk_bf16_f32 v0, -v0, s0
	v_lshl_add_u64 v[2:3], v[68:69], 0, v[2:3]
	global_store_short v[2:3], v0, off
	v_add_f32_e32 v0, v12, v74
	v_max_f32_e64 v6, -v0, 0
	v_mul_f32_e64 v0, |v0|, s4
	v_exp_f32_e32 v0, v0
	s_nop 0
	v_add_f32_e32 v4, 1.0, v0
	v_add_f32_e32 v5, -1.0, v4
	v_log_f32_e32 v7, v4
	v_rcp_f32_e32 v8, v4
	v_sub_f32_e32 v5, v0, v5
	v_mul_f32_e32 v5, v5, v8
	v_fmamk_f32 v0, v7, 0x3f317218, v5
	v_add_f32_e32 v0, v6, v0
	v_sub_f32_e32 v0, -0.5, v0
	v_mul_f32_e32 v0, 0x3fb8aa3b, v0
	v_exp_f32_e32 v0, v0
	s_nop 0
	v_cvt_pk_bf16_f32 v0, -v0, s0
	global_store_short v[2:3], v0, off offset:64
	v_add_f32_e32 v0, v29, v75
	v_max_f32_e64 v4, -v0, 0
	v_mul_f32_e64 v0, |v0|, s4
	v_exp_f32_e32 v0, v0
	s_nop 0
	v_add_f32_e32 v2, 1.0, v0
	v_add_f32_e32 v3, -1.0, v2
	v_log_f32_e32 v5, v2
	v_rcp_f32_e32 v6, v2
	v_sub_f32_e32 v3, v0, v3
	v_mul_f32_e32 v3, v3, v6
	v_fmamk_f32 v0, v5, 0x3f317218, v3
	v_add_f32_e32 v0, v4, v0
	v_sub_f32_e32 v0, -0.5, v0
	v_mul_f32_e32 v0, 0x3fb8aa3b, v0
	v_exp_f32_e32 v0, v0
	v_or_b32_e32 v2, 51, v66
	v_ashrrev_i32_e32 v3, 31, v2
	v_lshlrev_b64 v[2:3], 10, v[2:3]
	v_cvt_pk_bf16_f32 v0, -v0, s0
	v_lshl_add_u64 v[2:3], v[68:69], 0, v[2:3]
	global_store_short v[2:3], v0, off
	v_add_f32_e32 v0, v13, v74
	v_max_f32_e64 v6, -v0, 0
	v_mul_f32_e64 v0, |v0|, s4
	v_exp_f32_e32 v0, v0
	s_nop 0
	v_add_f32_e32 v4, 1.0, v0
	v_add_f32_e32 v5, -1.0, v4
	v_log_f32_e32 v7, v4
	v_rcp_f32_e32 v8, v4
	v_sub_f32_e32 v5, v0, v5
	v_mul_f32_e32 v5, v5, v8
	v_fmamk_f32 v0, v7, 0x3f317218, v5
	v_add_f32_e32 v0, v6, v0
	v_sub_f32_e32 v0, -0.5, v0
	v_mul_f32_e32 v0, 0x3fb8aa3b, v0
	v_exp_f32_e32 v0, v0
	s_nop 0
	v_cvt_pk_bf16_f32 v0, -v0, s0
	global_store_short v[2:3], v0, off offset:64
	v_add_f32_e32 v0, v30, v75
	v_max_f32_e64 v3, -v0, 0
	v_mul_f32_e64 v0, |v0|, s4
	v_exp_f32_e32 v0, v0
	v_or_b32_e32 v2, 56, v66
	v_add_f32_e32 v4, 1.0, v0
	v_add_f32_e32 v5, -1.0, v4
	v_log_f32_e32 v6, v4
	v_rcp_f32_e32 v7, v4
	v_sub_f32_e32 v5, v0, v5
	v_mul_f32_e32 v5, v5, v7
	v_fmamk_f32 v0, v6, 0x3f317218, v5
	v_add_f32_e32 v0, v3, v0
	v_sub_f32_e32 v0, -0.5, v0
	v_mul_f32_e32 v0, 0x3fb8aa3b, v0
	v_exp_f32_e32 v0, v0
	v_ashrrev_i32_e32 v3, 31, v2
	v_lshlrev_b64 v[2:3], 10, v[2:3]
	v_lshl_add_u64 v[2:3], v[68:69], 0, v[2:3]
	v_cvt_pk_bf16_f32 v0, -v0, s0
	global_store_short v[2:3], v0, off
	v_add_f32_e32 v0, v14, v74
	v_max_f32_e64 v6, -v0, 0
	v_mul_f32_e64 v0, |v0|, s4
	v_exp_f32_e32 v0, v0
	s_nop 0
	v_add_f32_e32 v4, 1.0, v0
	v_add_f32_e32 v5, -1.0, v4
	v_log_f32_e32 v7, v4
	v_rcp_f32_e32 v8, v4
	v_sub_f32_e32 v5, v0, v5
	v_mul_f32_e32 v5, v5, v8
	v_fmamk_f32 v0, v7, 0x3f317218, v5
	v_add_f32_e32 v0, v6, v0
	v_sub_f32_e32 v0, -0.5, v0
	v_mul_f32_e32 v0, 0x3fb8aa3b, v0
	v_exp_f32_e32 v0, v0
	s_nop 0
	v_cvt_pk_bf16_f32 v0, -v0, s0
	global_store_short v[2:3], v0, off offset:64
	v_add_f32_e32 v0, v31, v75
	v_max_f32_e64 v4, -v0, 0
	v_mul_f32_e64 v0, |v0|, s4
	v_exp_f32_e32 v0, v0
	s_nop 0
	v_add_f32_e32 v2, 1.0, v0
	v_add_f32_e32 v3, -1.0, v2
	v_log_f32_e32 v5, v2
	v_rcp_f32_e32 v6, v2
	v_sub_f32_e32 v3, v0, v3
	v_mul_f32_e32 v3, v3, v6
	v_fmamk_f32 v0, v5, 0x3f317218, v3
	v_add_f32_e32 v0, v4, v0
	v_sub_f32_e32 v0, -0.5, v0
	v_mul_f32_e32 v0, 0x3fb8aa3b, v0
	v_exp_f32_e32 v0, v0
	v_or_b32_e32 v2, 57, v66
	v_ashrrev_i32_e32 v3, 31, v2
	v_lshlrev_b64 v[2:3], 10, v[2:3]
	v_cvt_pk_bf16_f32 v0, -v0, s0
	v_lshl_add_u64 v[2:3], v[68:69], 0, v[2:3]
	global_store_short v[2:3], v0, off
	v_add_f32_e32 v0, v15, v74
	v_max_f32_e64 v6, -v0, 0
	v_mul_f32_e64 v0, |v0|, s4
	v_exp_f32_e32 v0, v0
	s_nop 0
	v_add_f32_e32 v4, 1.0, v0
	v_add_f32_e32 v5, -1.0, v4
	v_log_f32_e32 v7, v4
	v_rcp_f32_e32 v8, v4
	v_sub_f32_e32 v5, v0, v5
	v_mul_f32_e32 v5, v5, v8
	v_fmamk_f32 v0, v7, 0x3f317218, v5
	v_add_f32_e32 v0, v6, v0
	v_sub_f32_e32 v0, -0.5, v0
	v_mul_f32_e32 v0, 0x3fb8aa3b, v0
	v_exp_f32_e32 v0, v0
	s_nop 0
	v_cvt_pk_bf16_f32 v0, -v0, s0
	global_store_short v[2:3], v0, off offset:64
	v_add_f32_e32 v0, v32, v75
	v_max_f32_e64 v4, -v0, 0
	v_mul_f32_e64 v0, |v0|, s4
	v_exp_f32_e32 v0, v0
	s_nop 0
	v_add_f32_e32 v2, 1.0, v0
	v_add_f32_e32 v3, -1.0, v2
	v_log_f32_e32 v5, v2
	v_rcp_f32_e32 v6, v2
	v_sub_f32_e32 v3, v0, v3
	v_mul_f32_e32 v3, v3, v6
	v_fmamk_f32 v0, v5, 0x3f317218, v3
	v_add_f32_e32 v0, v4, v0
	v_sub_f32_e32 v0, -0.5, v0
	v_mul_f32_e32 v0, 0x3fb8aa3b, v0
	v_exp_f32_e32 v0, v0
	v_or_b32_e32 v2, 58, v66
	v_ashrrev_i32_e32 v3, 31, v2
	v_lshlrev_b64 v[2:3], 10, v[2:3]
	v_cvt_pk_bf16_f32 v0, -v0, s0
	v_lshl_add_u64 v[2:3], v[68:69], 0, v[2:3]
	global_store_short v[2:3], v0, off
	v_add_f32_e32 v0, v16, v74
	v_max_f32_e64 v6, -v0, 0
	v_mul_f32_e64 v0, |v0|, s4
	v_exp_f32_e32 v0, v0
	s_nop 0
	v_add_f32_e32 v4, 1.0, v0
	v_add_f32_e32 v5, -1.0, v4
	v_log_f32_e32 v7, v4
	v_rcp_f32_e32 v8, v4
	v_sub_f32_e32 v5, v0, v5
	v_mul_f32_e32 v5, v5, v8
	v_fmamk_f32 v0, v7, 0x3f317218, v5
	v_add_f32_e32 v0, v6, v0
	v_sub_f32_e32 v0, -0.5, v0
	v_mul_f32_e32 v0, 0x3fb8aa3b, v0
	v_exp_f32_e32 v0, v0
	s_nop 0
	v_cvt_pk_bf16_f32 v0, -v0, s0
	global_store_short v[2:3], v0, off offset:64
	v_add_f32_e32 v0, v33, v75
	v_max_f32_e64 v4, -v0, 0
	v_mul_f32_e64 v0, |v0|, s4
	v_exp_f32_e32 v0, v0
	s_nop 0
	v_add_f32_e32 v2, 1.0, v0
	v_add_f32_e32 v3, -1.0, v2
	v_log_f32_e32 v5, v2
	v_rcp_f32_e32 v6, v2
	v_sub_f32_e32 v3, v0, v3
	v_mul_f32_e32 v3, v3, v6
	v_fmamk_f32 v0, v5, 0x3f317218, v3
	v_add_f32_e32 v0, v4, v0
	v_sub_f32_e32 v0, -0.5, v0
	v_mul_f32_e32 v0, 0x3fb8aa3b, v0
	v_exp_f32_e32 v0, v0
	v_or_b32_e32 v2, 59, v66
	v_ashrrev_i32_e32 v3, 31, v2
	v_lshlrev_b64 v[2:3], 10, v[2:3]
	v_cvt_pk_bf16_f32 v0, -v0, s0
	v_lshl_add_u64 v[66:67], v[68:69], 0, v[2:3]
	global_store_short v[66:67], v0, off
	v_add_f32_e32 v0, v17, v74
	v_max_f32_e64 v16, -v0, 0
	v_mul_f32_e64 v0, |v0|, s4
	v_exp_f32_e32 v0, v0
	s_nop 0
	v_add_f32_e32 v2, 1.0, v0
	v_add_f32_e32 v3, -1.0, v2
	v_log_f32_e32 v4, v2
	v_rcp_f32_e32 v5, v2
	v_sub_f32_e32 v3, v0, v3
	v_mul_f32_e32 v3, v3, v5
	v_fmamk_f32 v0, v4, 0x3f317218, v3
	v_add_f32_e32 v0, v16, v0
	v_sub_f32_e32 v0, -0.5, v0
	v_mul_f32_e32 v0, 0x3fb8aa3b, v0
	v_exp_f32_e32 v0, v0
	s_nop 0
	v_cvt_pk_bf16_f32 v0, -v0, s0
